# hand-written epilogue of the out-proj main GEMM too: permlane16_swap pairing, dwordx4 stores (16 instead of 32 dwordx2), residual loads issued ahead of the stores
# baseline (speedup 1.0000x reference)
; __device__ __forceinline__ unsigned cvt_pk_bf16(float lo, float hi) { unsigned r; asm("v_cvt_pk_bf16_f32 %0, %1, %2" : "=v"(r) : "v"(lo), "v"(hi)); return r; }
;     __device__ __forceinline__ void operator()(const f32x4 (&acc)[2][2][4][2], const pg8::Unit& u, int wr, int wc, int fr, int fq) const {
;         const int row0 = u.pm * 256 + wr * 64 + fr, col0 = u.pn * 256 + wc * 32 + 4 * fq;
;         f32x4 swv[2][2];
; #pragma unroll
;         for (int bj = 0; bj < 2; ++bj)
; #pragma unroll
;             for (int n = 0; n < 2; ++n) swv[bj][n] = *(const f32x4*)(sw + col0 + bj * 128 + n * 16);
;         float sav[2][4];
; #pragma unroll
;         for (int ai = 0; ai < 2; ++ai)
; #pragma unroll
;             for (int m = 0; m < 4; ++m) sav[ai][m] = sa[row0 + ai * 128 + m * 16];
; #pragma unroll
;         for (int am = 0; am < 4; ++am) { const int ai = am >> 1, m0 = 2 * (am & 1); f32x4 r[2][2][2];
; #pragma unroll
;             for (int mm = 0; mm < 2; ++mm) { const int row = row0 + ai * 128 + (m0 + mm) * 16; const float* xin = (row < MP ? xp + (size_t)row * DM : xs + (size_t)(row - MP) * DM) + col0;
; #pragma unroll
;                 for (int bj = 0; bj < 2; ++bj)
; #pragma unroll
;                     for (int n = 0; n < 2; ++n) r[mm][bj][n] = *(const f32x4*)(xin + bj * 128 + n * 16); }
; #pragma unroll
;             for (int mm = 0; mm < 2; ++mm) { const size_t off = (size_t)(row0 + ai * 128 + (m0 + mm) * 16) * DM + col0;
; #pragma unroll
;                 for (int bj = 0; bj < 2; ++bj)
; #pragma unroll
;                     for (int n = 0; n < 2; ++n) { const i32x4 q = __builtin_bit_cast(i32x4, acc[ai][bj][m0 + mm][n]);
;                         const f32x4 v = (f32x4){(float)q[0], (float)q[1], (float)q[2], (float)q[3]} * swv[bj][n] * sav[ai][m0 + mm] + r[mm][bj][n];
;                         u32x2 w; w.x = cvt_pk_bf16(v[0], v[1]); w.y = cvt_pk_bf16(v[2], v[3]); *(u32x2*)(X1 + off + bj * 128 + n * 16) = w; } } }
;     }
.LBB0_2234:
	v_readlane_b32 s58, v254, 2
	v_readlane_b32 s59, v254, 3
	v_readlane_b32 s100, v254, 4
	v_readlane_b32 s101, v254, 5
	v_lshl_add_u32 v156, s28, 8, v163
	v_and_b32_e32 v157, 1, v235
	v_mul_u32_u24_e32 v157, 12, v157
	v_add_u32_e32 v157, v157, v165
	v_lshl_or_b32 v157, s56, 8, v157
	s_sub_u32 s100, s100, 0x8000000
	s_subb_u32 s101, s101, 0
	s_cmp_lt_i32 s28, 32
	s_cselect_b32 s58, s58, s100
	s_cselect_b32 s59, s59, s101
	v_lshlrev_b32_e32 v158, 2, v156
	v_lshlrev_b32_e32 v159, 2, v157
	v_lshlrev_b32_e32 v160, 13, v156
	v_lshl_add_u32 v160, v157, 1, v160
	v_lshlrev_b32_e32 v161, 14, v156
	v_lshl_add_u32 v161, v157, 2, v161
	global_load_dword v102, v158, s[6:7] offset:0
	global_load_dword v103, v158, s[6:7] offset:64
	global_load_dword v104, v158, s[6:7] offset:128
	global_load_dword v105, v158, s[6:7] offset:192
	global_load_dword v106, v158, s[6:7] offset:512
	global_load_dword v107, v158, s[6:7] offset:576
	global_load_dword v108, v158, s[6:7] offset:640
	global_load_dword v109, v158, s[6:7] offset:704
	global_load_dwordx4 v[114:117], v159, s[8:9] offset:0
	global_load_dwordx4 v[118:121], v159, s[8:9] offset:16
	global_load_dwordx4 v[170:173], v159, s[8:9] offset:512
	global_load_dwordx4 v[174:177], v159, s[8:9] offset:528
	v_mov_b32_e32 v162, v161
	global_load_dwordx4 v[178:181], v162, s[58:59] offset:0
	global_load_dwordx4 v[182:185], v162, s[58:59] offset:16
	v_mov_b32_e32 v231, v161
	global_load_dwordx4 v[186:189], v231, s[58:59] offset:512
	global_load_dwordx4 v[190:193], v231, s[58:59] offset:528
	v_add_u32_e32 v162, 0x40000, v161
	global_load_dwordx4 v[194:197], v162, s[58:59] offset:0
	global_load_dwordx4 v[198:201], v162, s[58:59] offset:16
	v_add_u32_e32 v231, 0x40000, v161
	global_load_dwordx4 v[202:205], v231, s[58:59] offset:512
	global_load_dwordx4 v[214:217], v231, s[58:59] offset:528
	v_add_u32_e32 v162, 0x80000, v161
	global_load_dwordx4 v[218:221], v162, s[58:59] offset:0
	global_load_dwordx4 v[222:225], v162, s[58:59] offset:16
	v_permlane16_swap_b32_e32 v142, v138
	v_permlane16_swap_b32_e32 v143, v139
	v_permlane16_swap_b32_e32 v144, v140
	v_permlane16_swap_b32_e32 v145, v141
	v_cvt_f32_i32_e32 v142, v142
	v_cvt_f32_i32_e32 v143, v143
	v_cvt_f32_i32_e32 v144, v144
	v_cvt_f32_i32_e32 v145, v145
	v_cvt_f32_i32_e32 v138, v138
	v_cvt_f32_i32_e32 v139, v139
	v_cvt_f32_i32_e32 v140, v140
	v_cvt_f32_i32_e32 v141, v141
	s_waitcnt vmcnt(8)
	v_pk_mul_f32 v[142:143], v[142:143], v[114:115]
	v_pk_mul_f32 v[144:145], v[144:145], v[116:117]
	v_pk_mul_f32 v[138:139], v[138:139], v[118:119]
	v_pk_mul_f32 v[140:141], v[140:141], v[120:121]
	v_fma_f32 v142, v142, v102, v178
	v_fma_f32 v143, v143, v102, v179
	v_fma_f32 v144, v144, v102, v180
	v_fma_f32 v145, v145, v102, v181
	v_fma_f32 v138, v138, v102, v182
	v_fma_f32 v139, v139, v102, v183
	v_fma_f32 v140, v140, v102, v184
	v_fma_f32 v141, v141, v102, v185
	v_cvt_pk_bf16_f32 v142, v142, v143
	v_cvt_pk_bf16_f32 v143, v144, v145
	v_cvt_pk_bf16_f32 v144, v138, v139
	v_cvt_pk_bf16_f32 v145, v140, v141
	v_permlane16_swap_b32_e32 v134, v130
	v_permlane16_swap_b32_e32 v135, v131
	v_permlane16_swap_b32_e32 v136, v132
	v_permlane16_swap_b32_e32 v137, v133
	v_cvt_f32_i32_e32 v134, v134
	v_cvt_f32_i32_e32 v135, v135
	v_cvt_f32_i32_e32 v136, v136
	v_cvt_f32_i32_e32 v137, v137
	v_cvt_f32_i32_e32 v130, v130
	v_cvt_f32_i32_e32 v131, v131
	v_cvt_f32_i32_e32 v132, v132
	v_cvt_f32_i32_e32 v133, v133
	s_waitcnt vmcnt(6)
	v_pk_mul_f32 v[134:135], v[134:135], v[170:171]
	v_pk_mul_f32 v[136:137], v[136:137], v[172:173]
	v_pk_mul_f32 v[130:131], v[130:131], v[174:175]
	v_pk_mul_f32 v[132:133], v[132:133], v[176:177]
	v_fma_f32 v134, v134, v102, v186
	v_fma_f32 v135, v135, v102, v187
	v_fma_f32 v136, v136, v102, v188
	v_fma_f32 v137, v137, v102, v189
	v_fma_f32 v130, v130, v102, v190
	v_fma_f32 v131, v131, v102, v191
	v_fma_f32 v132, v132, v102, v192
	v_fma_f32 v133, v133, v102, v193
	v_cvt_pk_bf16_f32 v134, v134, v135
	v_cvt_pk_bf16_f32 v135, v136, v137
	v_cvt_pk_bf16_f32 v136, v130, v131
	v_cvt_pk_bf16_f32 v137, v132, v133
	v_add_u32_e32 v231, 0x80000, v161
	global_load_dwordx4 v[138:141], v231, s[58:59] offset:512
	global_load_dwordx4 v[130:133], v231, s[58:59] offset:528
	v_permlane16_swap_b32_e32 v126, v122
	v_permlane16_swap_b32_e32 v127, v123
	v_permlane16_swap_b32_e32 v128, v124
	v_permlane16_swap_b32_e32 v129, v125
	v_cvt_f32_i32_e32 v126, v126
	v_cvt_f32_i32_e32 v127, v127
	v_cvt_f32_i32_e32 v128, v128
	v_cvt_f32_i32_e32 v129, v129
	v_cvt_f32_i32_e32 v122, v122
	v_cvt_f32_i32_e32 v123, v123
	v_cvt_f32_i32_e32 v124, v124
	v_cvt_f32_i32_e32 v125, v125
	s_waitcnt vmcnt(6)
	v_pk_mul_f32 v[126:127], v[126:127], v[114:115]
	v_pk_mul_f32 v[128:129], v[128:129], v[116:117]
	v_pk_mul_f32 v[122:123], v[122:123], v[118:119]
	v_pk_mul_f32 v[124:125], v[124:125], v[120:121]
	v_fma_f32 v126, v126, v103, v194
	v_fma_f32 v127, v127, v103, v195
	v_fma_f32 v128, v128, v103, v196
	v_fma_f32 v129, v129, v103, v197
	v_fma_f32 v122, v122, v103, v198
	v_fma_f32 v123, v123, v103, v199
	v_fma_f32 v124, v124, v103, v200
	v_fma_f32 v125, v125, v103, v201
	v_cvt_pk_bf16_f32 v126, v126, v127
	v_cvt_pk_bf16_f32 v127, v128, v129
	v_cvt_pk_bf16_f32 v128, v122, v123
	v_cvt_pk_bf16_f32 v129, v124, v125
	v_permlane16_swap_b32_e32 v110, v98
	v_permlane16_swap_b32_e32 v111, v99
	v_permlane16_swap_b32_e32 v112, v100
	v_permlane16_swap_b32_e32 v113, v101
	v_cvt_f32_i32_e32 v110, v110
	v_cvt_f32_i32_e32 v111, v111
	v_cvt_f32_i32_e32 v112, v112
	v_cvt_f32_i32_e32 v113, v113
	v_cvt_f32_i32_e32 v98, v98
	v_cvt_f32_i32_e32 v99, v99
	v_cvt_f32_i32_e32 v100, v100
	v_cvt_f32_i32_e32 v101, v101
	s_waitcnt vmcnt(4)
; __device__ __forceinline__ unsigned cvt_pk_bf16(float lo, float hi) { unsigned r; asm("v_cvt_pk_bf16_f32 %0, %1, %2" : "=v"(r) : "v"(lo), "v"(hi)); return r; }
;     __device__ __forceinline__ void operator()(const f32x4 (&acc)[2][2][4][2], const pg8::Unit& u, int wr, int wc, int fr, int fq) const {
;         const int row0 = u.pm * 256 + wr * 64 + fr, col0 = u.pn * 256 + wc * 32 + 4 * fq;
;         f32x4 swv[2][2];
; #pragma unroll
;         for (int bj = 0; bj < 2; ++bj)
; #pragma unroll
;             for (int n = 0; n < 2; ++n) swv[bj][n] = *(const f32x4*)(sw + col0 + bj * 128 + n * 16);
;         float sav[2][4];
; #pragma unroll
;         for (int ai = 0; ai < 2; ++ai)
; #pragma unroll
;             for (int m = 0; m < 4; ++m) sav[ai][m] = sa[row0 + ai * 128 + m * 16];
; #pragma unroll
;         for (int am = 0; am < 4; ++am) { const int ai = am >> 1, m0 = 2 * (am & 1); f32x4 r[2][2][2];
; #pragma unroll
;             for (int mm = 0; mm < 2; ++mm) { const int row = row0 + ai * 128 + (m0 + mm) * 16; const float* xin = (row < MP ? xp + (size_t)row * DM : xs + (size_t)(row - MP) * DM) + col0;
; #pragma unroll
;                 for (int bj = 0; bj < 2; ++bj)
; #pragma unroll
;                     for (int n = 0; n < 2; ++n) r[mm][bj][n] = *(const f32x4*)(xin + bj * 128 + n * 16); }
; #pragma unroll
;             for (int mm = 0; mm < 2; ++mm) { const size_t off = (size_t)(row0 + ai * 128 + (m0 + mm) * 16) * DM + col0;
; #pragma unroll
;                 for (int bj = 0; bj < 2; ++bj)
; #pragma unroll
;                     for (int n = 0; n < 2; ++n) { const i32x4 q = __builtin_bit_cast(i32x4, acc[ai][bj][m0 + mm][n]);
;                         const f32x4 v = (f32x4){(float)q[0], (float)q[1], (float)q[2], (float)q[3]} * swv[bj][n] * sav[ai][m0 + mm] + r[mm][bj][n];
;                         u32x2 w; w.x = cvt_pk_bf16(v[0], v[1]); w.y = cvt_pk_bf16(v[2], v[3]); *(u32x2*)(X1 + off + bj * 128 + n * 16) = w; } } }
;     }
	v_pk_mul_f32 v[110:111], v[110:111], v[170:171]
	v_pk_mul_f32 v[112:113], v[112:113], v[172:173]
	v_pk_mul_f32 v[98:99], v[98:99], v[174:175]
	v_pk_mul_f32 v[100:101], v[100:101], v[176:177]
	v_fma_f32 v110, v110, v103, v202
	v_fma_f32 v111, v111, v103, v203
	v_fma_f32 v112, v112, v103, v204
	v_fma_f32 v113, v113, v103, v205
	v_fma_f32 v98, v98, v103, v214
	v_fma_f32 v99, v99, v103, v215
	v_fma_f32 v100, v100, v103, v216
	v_fma_f32 v101, v101, v103, v217
	v_cvt_pk_bf16_f32 v110, v110, v111
	v_cvt_pk_bf16_f32 v111, v112, v113
	v_cvt_pk_bf16_f32 v112, v98, v99
	v_cvt_pk_bf16_f32 v113, v100, v101
	v_add_u32_e32 v162, 0xc0000, v161
	global_load_dwordx4 v[122:125], v162, s[58:59] offset:0
	global_load_dwordx4 v[98:101], v162, s[58:59] offset:16
	v_permlane16_swap_b32_e32 v94, v90
	v_permlane16_swap_b32_e32 v95, v91
	v_permlane16_swap_b32_e32 v96, v92
	v_permlane16_swap_b32_e32 v97, v93
	v_cvt_f32_i32_e32 v94, v94
	v_cvt_f32_i32_e32 v95, v95
	v_cvt_f32_i32_e32 v96, v96
	v_cvt_f32_i32_e32 v97, v97
	v_cvt_f32_i32_e32 v90, v90
	v_cvt_f32_i32_e32 v91, v91
	v_cvt_f32_i32_e32 v92, v92
	v_cvt_f32_i32_e32 v93, v93
	s_waitcnt vmcnt(4)
	v_pk_mul_f32 v[94:95], v[94:95], v[114:115]
	v_pk_mul_f32 v[96:97], v[96:97], v[116:117]
	v_pk_mul_f32 v[90:91], v[90:91], v[118:119]
	v_pk_mul_f32 v[92:93], v[92:93], v[120:121]
	v_fma_f32 v94, v94, v104, v218
	v_fma_f32 v95, v95, v104, v219
	v_fma_f32 v96, v96, v104, v220
	v_fma_f32 v97, v97, v104, v221
	v_fma_f32 v90, v90, v104, v222
	v_fma_f32 v91, v91, v104, v223
	v_fma_f32 v92, v92, v104, v224
	v_fma_f32 v93, v93, v104, v225
	v_cvt_pk_bf16_f32 v94, v94, v95
	v_cvt_pk_bf16_f32 v95, v96, v97
	v_cvt_pk_bf16_f32 v96, v90, v91
	v_cvt_pk_bf16_f32 v97, v92, v93
	v_add_u32_e32 v231, 0xc0000, v161
	global_load_dwordx4 v[178:181], v231, s[58:59] offset:512
	global_load_dwordx4 v[182:185], v231, s[58:59] offset:528
	v_permlane16_swap_b32_e32 v86, v78
	v_permlane16_swap_b32_e32 v87, v79
	v_permlane16_swap_b32_e32 v88, v80
	v_permlane16_swap_b32_e32 v89, v81
	v_cvt_f32_i32_e32 v86, v86
	v_cvt_f32_i32_e32 v87, v87
	v_cvt_f32_i32_e32 v88, v88
	v_cvt_f32_i32_e32 v89, v89
	v_cvt_f32_i32_e32 v78, v78
	v_cvt_f32_i32_e32 v79, v79
	v_cvt_f32_i32_e32 v80, v80
	v_cvt_f32_i32_e32 v81, v81
	s_waitcnt vmcnt(4)
	v_pk_mul_f32 v[86:87], v[86:87], v[170:171]
	v_pk_mul_f32 v[88:89], v[88:89], v[172:173]
	v_pk_mul_f32 v[78:79], v[78:79], v[174:175]
	v_pk_mul_f32 v[80:81], v[80:81], v[176:177]
	v_fma_f32 v86, v86, v104, v138
	v_fma_f32 v87, v87, v104, v139
	v_fma_f32 v88, v88, v104, v140
	v_fma_f32 v89, v89, v104, v141
	v_fma_f32 v78, v78, v104, v130
	v_fma_f32 v79, v79, v104, v131
	v_fma_f32 v80, v80, v104, v132
	v_fma_f32 v81, v81, v104, v133
	v_cvt_pk_bf16_f32 v86, v86, v87
	v_cvt_pk_bf16_f32 v87, v88, v89
	v_cvt_pk_bf16_f32 v88, v78, v79
	v_cvt_pk_bf16_f32 v89, v80, v81
	v_permlane16_swap_b32_e32 v82, v74
	v_permlane16_swap_b32_e32 v83, v75
	v_permlane16_swap_b32_e32 v84, v76
	v_permlane16_swap_b32_e32 v85, v77
	v_cvt_f32_i32_e32 v82, v82
	v_cvt_f32_i32_e32 v83, v83
	v_cvt_f32_i32_e32 v84, v84
	v_cvt_f32_i32_e32 v85, v85
	v_cvt_f32_i32_e32 v74, v74
	v_cvt_f32_i32_e32 v75, v75
	v_cvt_f32_i32_e32 v76, v76
	v_cvt_f32_i32_e32 v77, v77
	s_waitcnt vmcnt(2)
	v_pk_mul_f32 v[82:83], v[82:83], v[114:115]
	v_pk_mul_f32 v[84:85], v[84:85], v[116:117]
	v_pk_mul_f32 v[74:75], v[74:75], v[118:119]
	v_pk_mul_f32 v[76:77], v[76:77], v[120:121]
	v_fma_f32 v82, v82, v105, v122
	v_fma_f32 v83, v83, v105, v123
	v_fma_f32 v84, v84, v105, v124
	v_fma_f32 v85, v85, v105, v125
	v_fma_f32 v74, v74, v105, v98
	v_fma_f32 v75, v75, v105, v99
	v_fma_f32 v76, v76, v105, v100
	v_fma_f32 v77, v77, v105, v101
	v_cvt_pk_bf16_f32 v82, v82, v83
	v_cvt_pk_bf16_f32 v83, v84, v85
	v_cvt_pk_bf16_f32 v84, v74, v75
	v_cvt_pk_bf16_f32 v85, v76, v77
	v_permlane16_swap_b32_e32 v70, v66
	v_permlane16_swap_b32_e32 v71, v67
	v_permlane16_swap_b32_e32 v72, v68
	v_permlane16_swap_b32_e32 v73, v69
	v_cvt_f32_i32_e32 v70, v70
	v_cvt_f32_i32_e32 v71, v71
	v_cvt_f32_i32_e32 v72, v72
	v_cvt_f32_i32_e32 v73, v73
	v_cvt_f32_i32_e32 v66, v66
	v_cvt_f32_i32_e32 v67, v67
	v_cvt_f32_i32_e32 v68, v68
	v_cvt_f32_i32_e32 v69, v69
	s_waitcnt vmcnt(0)
	v_pk_mul_f32 v[70:71], v[70:71], v[170:171]
	v_pk_mul_f32 v[72:73], v[72:73], v[172:173]
	v_pk_mul_f32 v[66:67], v[66:67], v[174:175]
	v_pk_mul_f32 v[68:69], v[68:69], v[176:177]
	v_fma_f32 v70, v70, v105, v178
	v_fma_f32 v71, v71, v105, v179
	v_fma_f32 v72, v72, v105, v180
	v_fma_f32 v73, v73, v105, v181
	v_fma_f32 v66, v66, v105, v182
	v_fma_f32 v67, v67, v105, v183
	v_fma_f32 v68, v68, v105, v184
	v_fma_f32 v69, v69, v105, v185
	v_cvt_pk_bf16_f32 v70, v70, v71
	v_cvt_pk_bf16_f32 v71, v72, v73
	v_cvt_pk_bf16_f32 v72, v66, v67
	v_cvt_pk_bf16_f32 v73, v68, v69
	v_add_u32_e32 v162, 0x200000, v161
	global_load_dwordx4 v[178:181], v162, s[58:59] offset:0
	global_load_dwordx4 v[182:185], v162, s[58:59] offset:16
	v_add_u32_e32 v231, 0x200000, v161
	global_load_dwordx4 v[186:189], v231, s[58:59] offset:512
	global_load_dwordx4 v[190:193], v231, s[58:59] offset:528
	v_add_u32_e32 v162, 0x240000, v161
	global_load_dwordx4 v[194:197], v162, s[58:59] offset:0
	global_load_dwordx4 v[198:201], v162, s[58:59] offset:16
	v_add_u32_e32 v231, 0x240000, v161
	global_load_dwordx4 v[202:205], v231, s[58:59] offset:512
	global_load_dwordx4 v[214:217], v231, s[58:59] offset:528
	v_add_u32_e32 v162, 0x280000, v161
	global_load_dwordx4 v[218:221], v162, s[58:59] offset:0
	global_load_dwordx4 v[222:225], v162, s[58:59] offset:16
	v_add_u32_e32 v231, 0x280000, v161
	global_load_dwordx4 v[138:141], v231, s[58:59] offset:512
	global_load_dwordx4 v[130:133], v231, s[58:59] offset:528
; __device__ __forceinline__ unsigned cvt_pk_bf16(float lo, float hi) { unsigned r; asm("v_cvt_pk_bf16_f32 %0, %1, %2" : "=v"(r) : "v"(lo), "v"(hi)); return r; }
;     __device__ __forceinline__ void operator()(const f32x4 (&acc)[2][2][4][2], const pg8::Unit& u, int wr, int wc, int fr, int fq) const {
;         const int row0 = u.pm * 256 + wr * 64 + fr, col0 = u.pn * 256 + wc * 32 + 4 * fq;
;         f32x4 swv[2][2];
; #pragma unroll
;         for (int bj = 0; bj < 2; ++bj)
; #pragma unroll
;             for (int n = 0; n < 2; ++n) swv[bj][n] = *(const f32x4*)(sw + col0 + bj * 128 + n * 16);
;         float sav[2][4];
; #pragma unroll
;         for (int ai = 0; ai < 2; ++ai)
; #pragma unroll
;             for (int m = 0; m < 4; ++m) sav[ai][m] = sa[row0 + ai * 128 + m * 16];
; #pragma unroll
;         for (int am = 0; am < 4; ++am) { const int ai = am >> 1, m0 = 2 * (am & 1); f32x4 r[2][2][2];
; #pragma unroll
;             for (int mm = 0; mm < 2; ++mm) { const int row = row0 + ai * 128 + (m0 + mm) * 16; const float* xin = (row < MP ? xp + (size_t)row * DM : xs + (size_t)(row - MP) * DM) + col0;
; #pragma unroll
;                 for (int bj = 0; bj < 2; ++bj)
; #pragma unroll
;                     for (int n = 0; n < 2; ++n) r[mm][bj][n] = *(const f32x4*)(xin + bj * 128 + n * 16); }
; #pragma unroll
;             for (int mm = 0; mm < 2; ++mm) { const size_t off = (size_t)(row0 + ai * 128 + (m0 + mm) * 16) * DM + col0;
; #pragma unroll
;                 for (int bj = 0; bj < 2; ++bj)
; #pragma unroll
;                     for (int n = 0; n < 2; ++n) { const i32x4 q = __builtin_bit_cast(i32x4, acc[ai][bj][m0 + mm][n]);
;                         const f32x4 v = (f32x4){(float)q[0], (float)q[1], (float)q[2], (float)q[3]} * swv[bj][n] * sav[ai][m0 + mm] + r[mm][bj][n];
;                         u32x2 w; w.x = cvt_pk_bf16(v[0], v[1]); w.y = cvt_pk_bf16(v[2], v[3]); *(u32x2*)(X1 + off + bj * 128 + n * 16) = w; } } }
;     }
	v_add_u32_e32 v162, 0x2c0000, v161
	global_load_dwordx4 v[122:125], v162, s[58:59] offset:0
	global_load_dwordx4 v[98:101], v162, s[58:59] offset:16
	v_add_u32_e32 v231, 0x2c0000, v161
	global_load_dwordx4 v[90:93], v231, s[58:59] offset:512
	global_load_dwordx4 v[78:81], v231, s[58:59] offset:528
	v_mov_b32_e32 v162, v160
	global_store_dwordx4 v162, v[142:145], s[14:15] offset:0
	v_mov_b32_e32 v231, v160
	global_store_dwordx4 v231, v[134:137], s[14:15] offset:256
	v_add_u32_e32 v162, 0x20000, v160
	global_store_dwordx4 v162, v[126:129], s[14:15] offset:0
	v_add_u32_e32 v231, 0x20000, v160
	global_store_dwordx4 v231, v[110:113], s[14:15] offset:256
	v_add_u32_e32 v162, 0x40000, v160
	global_store_dwordx4 v162, v[94:97], s[14:15] offset:0
	v_add_u32_e32 v231, 0x40000, v160
	global_store_dwordx4 v231, v[86:89], s[14:15] offset:256
	v_add_u32_e32 v162, 0x60000, v160
	global_store_dwordx4 v162, v[82:85], s[14:15] offset:0
	v_add_u32_e32 v231, 0x60000, v160
	global_store_dwordx4 v231, v[70:73], s[14:15] offset:256
	v_permlane16_swap_b32_e32 v62, v58
	v_permlane16_swap_b32_e32 v63, v59
	v_permlane16_swap_b32_e32 v64, v60
	v_permlane16_swap_b32_e32 v65, v61
	v_cvt_f32_i32_e32 v62, v62
	v_cvt_f32_i32_e32 v63, v63
	v_cvt_f32_i32_e32 v64, v64
	v_cvt_f32_i32_e32 v65, v65
	v_cvt_f32_i32_e32 v58, v58
	v_cvt_f32_i32_e32 v59, v59
	v_cvt_f32_i32_e32 v60, v60
	v_cvt_f32_i32_e32 v61, v61
	s_waitcnt vmcnt(22)
	v_pk_mul_f32 v[62:63], v[62:63], v[114:115]
	v_pk_mul_f32 v[64:65], v[64:65], v[116:117]
	v_pk_mul_f32 v[58:59], v[58:59], v[118:119]
	v_pk_mul_f32 v[60:61], v[60:61], v[120:121]
	v_fma_f32 v62, v62, v106, v178
	v_fma_f32 v63, v63, v106, v179
	v_fma_f32 v64, v64, v106, v180
	v_fma_f32 v65, v65, v106, v181
	v_fma_f32 v58, v58, v106, v182
	v_fma_f32 v59, v59, v106, v183
	v_fma_f32 v60, v60, v106, v184
	v_fma_f32 v61, v61, v106, v185
	v_cvt_pk_bf16_f32 v62, v62, v63
	v_cvt_pk_bf16_f32 v63, v64, v65
	v_cvt_pk_bf16_f32 v64, v58, v59
	v_cvt_pk_bf16_f32 v65, v60, v61
	v_add_u32_e32 v162, 0x100000, v160
	global_store_dwordx4 v162, v[62:65], s[14:15] offset:0
	v_permlane16_swap_b32_e32 v54, v46
	v_permlane16_swap_b32_e32 v55, v47
	v_permlane16_swap_b32_e32 v56, v48
	v_permlane16_swap_b32_e32 v57, v49
	v_cvt_f32_i32_e32 v54, v54
	v_cvt_f32_i32_e32 v55, v55
	v_cvt_f32_i32_e32 v56, v56
	v_cvt_f32_i32_e32 v57, v57
	v_cvt_f32_i32_e32 v46, v46
	v_cvt_f32_i32_e32 v47, v47
	v_cvt_f32_i32_e32 v48, v48
	v_cvt_f32_i32_e32 v49, v49
	s_waitcnt vmcnt(21)
	v_pk_mul_f32 v[54:55], v[54:55], v[170:171]
	v_pk_mul_f32 v[56:57], v[56:57], v[172:173]
	v_pk_mul_f32 v[46:47], v[46:47], v[174:175]
	v_pk_mul_f32 v[48:49], v[48:49], v[176:177]
	v_fma_f32 v54, v54, v106, v186
	v_fma_f32 v55, v55, v106, v187
	v_fma_f32 v56, v56, v106, v188
	v_fma_f32 v57, v57, v106, v189
	v_fma_f32 v46, v46, v106, v190
	v_fma_f32 v47, v47, v106, v191
	v_fma_f32 v48, v48, v106, v192
	v_fma_f32 v49, v49, v106, v193
	v_cvt_pk_bf16_f32 v54, v54, v55
	v_cvt_pk_bf16_f32 v55, v56, v57
	v_cvt_pk_bf16_f32 v56, v46, v47
	v_cvt_pk_bf16_f32 v57, v48, v49
	v_add_u32_e32 v231, 0x100000, v160
	global_store_dwordx4 v231, v[54:57], s[14:15] offset:256
	v_permlane16_swap_b32_e32 v50, v42
	v_permlane16_swap_b32_e32 v51, v43
	v_permlane16_swap_b32_e32 v52, v44
	v_permlane16_swap_b32_e32 v53, v45
	v_cvt_f32_i32_e32 v50, v50
	v_cvt_f32_i32_e32 v51, v51
	v_cvt_f32_i32_e32 v52, v52
	v_cvt_f32_i32_e32 v53, v53
	v_cvt_f32_i32_e32 v42, v42
	v_cvt_f32_i32_e32 v43, v43
	v_cvt_f32_i32_e32 v44, v44
	v_cvt_f32_i32_e32 v45, v45
	s_waitcnt vmcnt(20)
	v_pk_mul_f32 v[50:51], v[50:51], v[114:115]
	v_pk_mul_f32 v[52:53], v[52:53], v[116:117]
	v_pk_mul_f32 v[42:43], v[42:43], v[118:119]
	v_pk_mul_f32 v[44:45], v[44:45], v[120:121]
	v_fma_f32 v50, v50, v107, v194
	v_fma_f32 v51, v51, v107, v195
	v_fma_f32 v52, v52, v107, v196
	v_fma_f32 v53, v53, v107, v197
	v_fma_f32 v42, v42, v107, v198
	v_fma_f32 v43, v43, v107, v199
	v_fma_f32 v44, v44, v107, v200
	v_fma_f32 v45, v45, v107, v201
	v_cvt_pk_bf16_f32 v50, v50, v51
	v_cvt_pk_bf16_f32 v51, v52, v53
	v_cvt_pk_bf16_f32 v52, v42, v43
	v_cvt_pk_bf16_f32 v53, v44, v45
	v_add_u32_e32 v162, 0x120000, v160
	global_store_dwordx4 v162, v[50:53], s[14:15] offset:0
	v_permlane16_swap_b32_e32 v38, v34
	v_permlane16_swap_b32_e32 v39, v35
	v_permlane16_swap_b32_e32 v40, v36
	v_permlane16_swap_b32_e32 v41, v37
	v_cvt_f32_i32_e32 v38, v38
	v_cvt_f32_i32_e32 v39, v39
	v_cvt_f32_i32_e32 v40, v40
	v_cvt_f32_i32_e32 v41, v41
	v_cvt_f32_i32_e32 v34, v34
	v_cvt_f32_i32_e32 v35, v35
	v_cvt_f32_i32_e32 v36, v36
	v_cvt_f32_i32_e32 v37, v37
	s_waitcnt vmcnt(19)
; __device__ __forceinline__ unsigned cvt_pk_bf16(float lo, float hi) { unsigned r; asm("v_cvt_pk_bf16_f32 %0, %1, %2" : "=v"(r) : "v"(lo), "v"(hi)); return r; }
;     __device__ __forceinline__ void operator()(const f32x4 (&acc)[2][2][4][2], const pg8::Unit& u, int wr, int wc, int fr, int fq) const {
;         const int row0 = u.pm * 256 + wr * 64 + fr, col0 = u.pn * 256 + wc * 32 + 4 * fq;
;         f32x4 swv[2][2];
; #pragma unroll
;         for (int bj = 0; bj < 2; ++bj)
; #pragma unroll
;             for (int n = 0; n < 2; ++n) swv[bj][n] = *(const f32x4*)(sw + col0 + bj * 128 + n * 16);
;         float sav[2][4];
; #pragma unroll
;         for (int ai = 0; ai < 2; ++ai)
; #pragma unroll
;             for (int m = 0; m < 4; ++m) sav[ai][m] = sa[row0 + ai * 128 + m * 16];
; #pragma unroll
;         for (int am = 0; am < 4; ++am) { const int ai = am >> 1, m0 = 2 * (am & 1); f32x4 r[2][2][2];
; #pragma unroll
;             for (int mm = 0; mm < 2; ++mm) { const int row = row0 + ai * 128 + (m0 + mm) * 16; const float* xin = (row < MP ? xp + (size_t)row * DM : xs + (size_t)(row - MP) * DM) + col0;
; #pragma unroll
;                 for (int bj = 0; bj < 2; ++bj)
; #pragma unroll
;                     for (int n = 0; n < 2; ++n) r[mm][bj][n] = *(const f32x4*)(xin + bj * 128 + n * 16); }
; #pragma unroll
;             for (int mm = 0; mm < 2; ++mm) { const size_t off = (size_t)(row0 + ai * 128 + (m0 + mm) * 16) * DM + col0;
; #pragma unroll
;                 for (int bj = 0; bj < 2; ++bj)
; #pragma unroll
;                     for (int n = 0; n < 2; ++n) { const i32x4 q = __builtin_bit_cast(i32x4, acc[ai][bj][m0 + mm][n]);
;                         const f32x4 v = (f32x4){(float)q[0], (float)q[1], (float)q[2], (float)q[3]} * swv[bj][n] * sav[ai][m0 + mm] + r[mm][bj][n];
;                         u32x2 w; w.x = cvt_pk_bf16(v[0], v[1]); w.y = cvt_pk_bf16(v[2], v[3]); *(u32x2*)(X1 + off + bj * 128 + n * 16) = w; } } }
;     }
	v_pk_mul_f32 v[38:39], v[38:39], v[170:171]
	v_pk_mul_f32 v[40:41], v[40:41], v[172:173]
	v_pk_mul_f32 v[34:35], v[34:35], v[174:175]
	v_pk_mul_f32 v[36:37], v[36:37], v[176:177]
	v_fma_f32 v38, v38, v107, v202
	v_fma_f32 v39, v39, v107, v203
	v_fma_f32 v40, v40, v107, v204
	v_fma_f32 v41, v41, v107, v205
	v_fma_f32 v34, v34, v107, v214
	v_fma_f32 v35, v35, v107, v215
	v_fma_f32 v36, v36, v107, v216
	v_fma_f32 v37, v37, v107, v217
	v_cvt_pk_bf16_f32 v38, v38, v39
	v_cvt_pk_bf16_f32 v39, v40, v41
	v_cvt_pk_bf16_f32 v40, v34, v35
	v_cvt_pk_bf16_f32 v41, v36, v37
	v_add_u32_e32 v231, 0x120000, v160
	global_store_dwordx4 v231, v[38:41], s[14:15] offset:256
	v_permlane16_swap_b32_e32 v30, v26
	v_permlane16_swap_b32_e32 v31, v27
	v_permlane16_swap_b32_e32 v32, v28
	v_permlane16_swap_b32_e32 v33, v29
	v_cvt_f32_i32_e32 v30, v30
	v_cvt_f32_i32_e32 v31, v31
	v_cvt_f32_i32_e32 v32, v32
	v_cvt_f32_i32_e32 v33, v33
	v_cvt_f32_i32_e32 v26, v26
	v_cvt_f32_i32_e32 v27, v27
	v_cvt_f32_i32_e32 v28, v28
	v_cvt_f32_i32_e32 v29, v29
	s_waitcnt vmcnt(18)
	v_pk_mul_f32 v[30:31], v[30:31], v[114:115]
	v_pk_mul_f32 v[32:33], v[32:33], v[116:117]
	v_pk_mul_f32 v[26:27], v[26:27], v[118:119]
	v_pk_mul_f32 v[28:29], v[28:29], v[120:121]
	v_fma_f32 v30, v30, v108, v218
	v_fma_f32 v31, v31, v108, v219
	v_fma_f32 v32, v32, v108, v220
	v_fma_f32 v33, v33, v108, v221
	v_fma_f32 v26, v26, v108, v222
	v_fma_f32 v27, v27, v108, v223
	v_fma_f32 v28, v28, v108, v224
	v_fma_f32 v29, v29, v108, v225
	v_cvt_pk_bf16_f32 v30, v30, v31
	v_cvt_pk_bf16_f32 v31, v32, v33
	v_cvt_pk_bf16_f32 v32, v26, v27
	v_cvt_pk_bf16_f32 v33, v28, v29
	v_add_u32_e32 v162, 0x140000, v160
	global_store_dwordx4 v162, v[30:33], s[14:15] offset:0
	v_permlane16_swap_b32_e32 v22, v14
	v_permlane16_swap_b32_e32 v23, v15
	v_permlane16_swap_b32_e32 v24, v16
	v_permlane16_swap_b32_e32 v25, v17
	v_cvt_f32_i32_e32 v22, v22
	v_cvt_f32_i32_e32 v23, v23
	v_cvt_f32_i32_e32 v24, v24
	v_cvt_f32_i32_e32 v25, v25
	v_cvt_f32_i32_e32 v14, v14
	v_cvt_f32_i32_e32 v15, v15
	v_cvt_f32_i32_e32 v16, v16
	v_cvt_f32_i32_e32 v17, v17
	s_waitcnt vmcnt(17)
	v_pk_mul_f32 v[22:23], v[22:23], v[170:171]
	v_pk_mul_f32 v[24:25], v[24:25], v[172:173]
	v_pk_mul_f32 v[14:15], v[14:15], v[174:175]
	v_pk_mul_f32 v[16:17], v[16:17], v[176:177]
	v_fma_f32 v22, v22, v108, v138
	v_fma_f32 v23, v23, v108, v139
	v_fma_f32 v24, v24, v108, v140
	v_fma_f32 v25, v25, v108, v141
	v_fma_f32 v14, v14, v108, v130
	v_fma_f32 v15, v15, v108, v131
	v_fma_f32 v16, v16, v108, v132
	v_fma_f32 v17, v17, v108, v133
	v_cvt_pk_bf16_f32 v22, v22, v23
	v_cvt_pk_bf16_f32 v23, v24, v25
	v_cvt_pk_bf16_f32 v24, v14, v15
	v_cvt_pk_bf16_f32 v25, v16, v17
	v_add_u32_e32 v231, 0x140000, v160
	global_store_dwordx4 v231, v[22:25], s[14:15] offset:256
	v_permlane16_swap_b32_e32 v18, v10
	v_permlane16_swap_b32_e32 v19, v11
	v_permlane16_swap_b32_e32 v20, v12
	v_permlane16_swap_b32_e32 v21, v13
	v_cvt_f32_i32_e32 v18, v18
	v_cvt_f32_i32_e32 v19, v19
	v_cvt_f32_i32_e32 v20, v20
	v_cvt_f32_i32_e32 v21, v21
	v_cvt_f32_i32_e32 v10, v10
	v_cvt_f32_i32_e32 v11, v11
	v_cvt_f32_i32_e32 v12, v12
	v_cvt_f32_i32_e32 v13, v13
	s_waitcnt vmcnt(16)
	v_pk_mul_f32 v[18:19], v[18:19], v[114:115]
	v_pk_mul_f32 v[20:21], v[20:21], v[116:117]
	v_pk_mul_f32 v[10:11], v[10:11], v[118:119]
	v_pk_mul_f32 v[12:13], v[12:13], v[120:121]
	v_fma_f32 v18, v18, v109, v122
	v_fma_f32 v19, v19, v109, v123
	v_fma_f32 v20, v20, v109, v124
	v_fma_f32 v21, v21, v109, v125
	v_fma_f32 v10, v10, v109, v98
	v_fma_f32 v11, v11, v109, v99
	v_fma_f32 v12, v12, v109, v100
	v_fma_f32 v13, v13, v109, v101
	v_cvt_pk_bf16_f32 v18, v18, v19
	v_cvt_pk_bf16_f32 v19, v20, v21
	v_cvt_pk_bf16_f32 v20, v10, v11
	v_cvt_pk_bf16_f32 v21, v12, v13
	v_add_u32_e32 v162, 0x160000, v160
	global_store_dwordx4 v162, v[18:21], s[14:15] offset:0
	v_permlane16_swap_b32_e32 v6, v2
	v_permlane16_swap_b32_e32 v7, v3
	v_permlane16_swap_b32_e32 v8, v4
	v_permlane16_swap_b32_e32 v9, v5
	v_cvt_f32_i32_e32 v6, v6
	v_cvt_f32_i32_e32 v7, v7
	v_cvt_f32_i32_e32 v8, v8
	v_cvt_f32_i32_e32 v9, v9
	v_cvt_f32_i32_e32 v2, v2
	v_cvt_f32_i32_e32 v3, v3
	v_cvt_f32_i32_e32 v4, v4
	v_cvt_f32_i32_e32 v5, v5
	s_waitcnt vmcnt(15)
	v_pk_mul_f32 v[6:7], v[6:7], v[170:171]
	v_pk_mul_f32 v[8:9], v[8:9], v[172:173]
	v_pk_mul_f32 v[2:3], v[2:3], v[174:175]
	v_pk_mul_f32 v[4:5], v[4:5], v[176:177]
	v_fma_f32 v6, v6, v109, v90
	v_fma_f32 v7, v7, v109, v91
	v_fma_f32 v8, v8, v109, v92
	v_fma_f32 v9, v9, v109, v93
	v_fma_f32 v2, v2, v109, v78
	v_fma_f32 v3, v3, v109, v79
	v_fma_f32 v4, v4, v109, v80
	v_fma_f32 v5, v5, v109, v81
	v_cvt_pk_bf16_f32 v6, v6, v7
	v_cvt_pk_bf16_f32 v7, v8, v9
	v_cvt_pk_bf16_f32 v8, v2, v3
	v_cvt_pk_bf16_f32 v9, v4, v5
	v_add_u32_e32 v231, 0x160000, v160
	global_store_dwordx4 v231, v[6:9], s[14:15] offset:256
	s_andn2_b64 vcc, exec, s[4:5]
	s_mov_b64 s[4:5], -1
	s_cbranch_vccnz .LBB0_2227
	s_andn2_b64 vcc, exec, s[12:13]
	s_cbranch_vccnz .LBB0_2226
	s_barrier
	s_branch .LBB0_2226
